# MLP-in epilogue stores (P4/P12, 128 MB of hb each) marked sc1 (write-through): less dirty L2 to write back at the phase seam
# baseline (speedup 1.0000x reference)
.LBB0_465:
	v_lshl_add_u32 v150, s0, 8, v1
	v_ashrrev_i32_e32 v151, 31, v150
	v_lshl_add_u64 v[148:149], v[150:151], 2, s[72:73]
	global_load_dword v152, v[148:149], off
	v_lshlrev_b64 v[160:161], 13, v[150:151]
	v_lshl_or_b32 v146, s1, 8, v155
	v_ashrrev_i32_e32 v147, 31, v146
	s_waitcnt vmcnt(0)
	v_fmamk_f32 v151, v152, 0x3a800000, v159
	v_rsq_f32_e32 v162, v151
	v_lshlrev_b64 v[152:153], 1, v[146:147]
	v_lshl_add_u64 v[146:147], s[38:39], 0, v[160:161]
	v_lshl_add_u64 v[146:147], v[146:147], 0, v[152:153]
	v_pk_mul_f32 v[128:129], v[128:129], v[162:163] op_sel_hi:[1,0]
	v_pk_mul_f32 v[126:127], v[126:127], v[162:163] op_sel_hi:[1,0]
	v_pk_mul_f32 v[124:125], v[124:125], v[162:163] op_sel_hi:[1,0]
	v_pk_mul_f32 v[122:123], v[122:123], v[162:163] op_sel_hi:[1,0]
	v_pk_mul_f32 v[120:121], v[120:121], v[162:163] op_sel_hi:[1,0]
	v_pk_mul_f32 v[118:119], v[118:119], v[162:163] op_sel_hi:[1,0]
	v_pk_mul_f32 v[116:117], v[116:117], v[162:163] op_sel_hi:[1,0]
	v_pk_mul_f32 v[114:115], v[114:115], v[162:163] op_sel_hi:[1,0]
	v_max_f32_e32 v126, 0, v126
	v_max_f32_e32 v122, 0, v122
	v_max_f32_e32 v127, 0, v127
	v_max_f32_e32 v123, 0, v123
	v_max_f32_e32 v128, 0, v128
	v_max_f32_e32 v124, 0, v124
	v_max_f32_e32 v129, 0, v129
	v_max_f32_e32 v125, 0, v125
	v_max_f32_e32 v118, 0, v118
	v_max_f32_e32 v114, 0, v114
	v_max_f32_e32 v119, 0, v119
	v_max_f32_e32 v115, 0, v115
	v_max_f32_e32 v120, 0, v120
	v_max_f32_e32 v116, 0, v116
	v_max_f32_e32 v121, 0, v121
	v_max_f32_e32 v117, 0, v117
	v_pk_mul_f32 v[126:127], v[126:127], v[126:127]
	v_pk_mul_f32 v[122:123], v[122:123], v[122:123]
	v_pk_mul_f32 v[128:129], v[128:129], v[128:129]
	v_pk_mul_f32 v[124:125], v[124:125], v[124:125]
	v_pk_mul_f32 v[118:119], v[118:119], v[118:119]
	v_pk_mul_f32 v[160:161], v[114:115], v[114:115]
	v_pk_mul_f32 v[120:121], v[120:121], v[120:121]
	v_pk_mul_f32 v[162:163], v[116:117], v[116:117]
	v_cvt_pk_bf16_f32 v114, v126, v127
	v_cvt_pk_bf16_f32 v115, v128, v129
	v_cvt_pk_bf16_f32 v116, v122, v123
	v_cvt_pk_bf16_f32 v117, v124, v125
	v_cvt_pk_bf16_f32 v118, v118, v119
	v_cvt_pk_bf16_f32 v119, v120, v121
	v_cvt_pk_bf16_f32 v120, v160, v161
	v_cvt_pk_bf16_f32 v121, v162, v163
	global_store_dwordx4 v[146:147], v[114:117], off sc1
	global_store_dwordx4 v[146:147], v[118:121], off offset:256 sc1
	global_load_dword v116, v[148:149], off offset:64
	v_or_b32_e32 v114, 16, v150
	v_ashrrev_i32_e32 v115, 31, v114
	v_lshlrev_b64 v[114:115], 13, v[114:115]
	v_lshl_add_u64 v[114:115], s[38:39], 0, v[114:115]
	v_lshl_add_u64 v[114:115], v[114:115], 0, v[152:153]
	s_waitcnt vmcnt(0)
	v_fmamk_f32 v116, v116, 0x3a800000, v159
	v_rsq_f32_e32 v116, v116
	s_nop 0
	v_pk_mul_f32 v[112:113], v[112:113], v[116:117] op_sel_hi:[1,0]
	v_pk_mul_f32 v[110:111], v[110:111], v[116:117] op_sel_hi:[1,0]
	v_pk_mul_f32 v[108:109], v[108:109], v[116:117] op_sel_hi:[1,0]
	v_pk_mul_f32 v[106:107], v[106:107], v[116:117] op_sel_hi:[1,0]
	v_pk_mul_f32 v[104:105], v[104:105], v[116:117] op_sel_hi:[1,0]
	v_pk_mul_f32 v[102:103], v[102:103], v[116:117] op_sel_hi:[1,0]
	v_pk_mul_f32 v[100:101], v[100:101], v[116:117] op_sel_hi:[1,0]
	v_pk_mul_f32 v[98:99], v[98:99], v[116:117] op_sel_hi:[1,0]
	v_max_f32_e32 v110, 0, v110
	v_max_f32_e32 v106, 0, v106
	v_max_f32_e32 v111, 0, v111
	v_max_f32_e32 v107, 0, v107
	v_max_f32_e32 v112, 0, v112
	v_max_f32_e32 v108, 0, v108
	v_max_f32_e32 v113, 0, v113
	v_max_f32_e32 v109, 0, v109
	v_max_f32_e32 v102, 0, v102
	v_max_f32_e32 v98, 0, v98
	v_max_f32_e32 v103, 0, v103
	v_max_f32_e32 v99, 0, v99
	v_max_f32_e32 v104, 0, v104
	v_max_f32_e32 v100, 0, v100
	v_max_f32_e32 v105, 0, v105
	v_max_f32_e32 v101, 0, v101
	v_pk_mul_f32 v[110:111], v[110:111], v[110:111]
	v_pk_mul_f32 v[106:107], v[106:107], v[106:107]
	v_pk_mul_f32 v[112:113], v[112:113], v[112:113]
	v_pk_mul_f32 v[108:109], v[108:109], v[108:109]
	v_pk_mul_f32 v[102:103], v[102:103], v[102:103]
	v_pk_mul_f32 v[116:117], v[98:99], v[98:99]
	v_pk_mul_f32 v[104:105], v[104:105], v[104:105]
	v_pk_mul_f32 v[118:119], v[100:101], v[100:101]
	v_cvt_pk_bf16_f32 v98, v110, v111
	v_cvt_pk_bf16_f32 v99, v112, v113
	v_cvt_pk_bf16_f32 v100, v106, v107
	v_cvt_pk_bf16_f32 v101, v108, v109
	v_cvt_pk_bf16_f32 v102, v102, v103
	v_cvt_pk_bf16_f32 v103, v104, v105
	v_cvt_pk_bf16_f32 v104, v116, v117
	v_cvt_pk_bf16_f32 v105, v118, v119
	global_store_dwordx4 v[114:115], v[98:101], off sc1
	global_store_dwordx4 v[114:115], v[102:105], off offset:256 sc1
	global_load_dword v100, v[148:149], off offset:128
	v_or_b32_e32 v98, 32, v150
	v_ashrrev_i32_e32 v99, 31, v98
	v_lshlrev_b64 v[98:99], 13, v[98:99]
	v_lshl_add_u64 v[98:99], s[38:39], 0, v[98:99]
	v_lshl_add_u64 v[98:99], v[98:99], 0, v[152:153]
	s_waitcnt vmcnt(0)
	v_fmamk_f32 v100, v100, 0x3a800000, v159
	v_rsq_f32_e32 v100, v100
	s_nop 0
	v_pk_mul_f32 v[96:97], v[96:97], v[100:101] op_sel_hi:[1,0]
	v_pk_mul_f32 v[94:95], v[94:95], v[100:101] op_sel_hi:[1,0]
	v_pk_mul_f32 v[92:93], v[92:93], v[100:101] op_sel_hi:[1,0]
	v_pk_mul_f32 v[90:91], v[90:91], v[100:101] op_sel_hi:[1,0]
	v_pk_mul_f32 v[88:89], v[88:89], v[100:101] op_sel_hi:[1,0]
	v_pk_mul_f32 v[86:87], v[86:87], v[100:101] op_sel_hi:[1,0]
	v_pk_mul_f32 v[84:85], v[84:85], v[100:101] op_sel_hi:[1,0]
	v_pk_mul_f32 v[82:83], v[82:83], v[100:101] op_sel_hi:[1,0]
	v_max_f32_e32 v94, 0, v94
	v_max_f32_e32 v90, 0, v90
	v_max_f32_e32 v95, 0, v95
	v_max_f32_e32 v91, 0, v91
	v_max_f32_e32 v96, 0, v96
	v_max_f32_e32 v92, 0, v92
	v_max_f32_e32 v97, 0, v97
	v_max_f32_e32 v93, 0, v93
	v_max_f32_e32 v86, 0, v86
	v_max_f32_e32 v82, 0, v82
	v_max_f32_e32 v87, 0, v87
	v_max_f32_e32 v83, 0, v83
	v_max_f32_e32 v88, 0, v88
	v_max_f32_e32 v84, 0, v84
	v_max_f32_e32 v89, 0, v89
	v_max_f32_e32 v85, 0, v85
	v_pk_mul_f32 v[94:95], v[94:95], v[94:95]
	v_pk_mul_f32 v[90:91], v[90:91], v[90:91]
	v_pk_mul_f32 v[96:97], v[96:97], v[96:97]
	v_pk_mul_f32 v[92:93], v[92:93], v[92:93]
	v_pk_mul_f32 v[86:87], v[86:87], v[86:87]
	v_pk_mul_f32 v[100:101], v[82:83], v[82:83]
	v_pk_mul_f32 v[88:89], v[88:89], v[88:89]
	v_pk_mul_f32 v[102:103], v[84:85], v[84:85]
	v_cvt_pk_bf16_f32 v82, v94, v95
	v_cvt_pk_bf16_f32 v83, v96, v97
	v_cvt_pk_bf16_f32 v84, v90, v91
	v_cvt_pk_bf16_f32 v85, v92, v93
	v_cvt_pk_bf16_f32 v86, v86, v87
	v_cvt_pk_bf16_f32 v87, v88, v89
	v_cvt_pk_bf16_f32 v88, v100, v101
	v_cvt_pk_bf16_f32 v89, v102, v103
	global_store_dwordx4 v[98:99], v[82:85], off sc1
	global_store_dwordx4 v[98:99], v[86:89], off offset:256 sc1
	global_load_dword v84, v[148:149], off offset:192
	v_or_b32_e32 v82, 48, v150
	v_ashrrev_i32_e32 v83, 31, v82
	v_lshlrev_b64 v[82:83], 13, v[82:83]
	v_lshl_add_u64 v[82:83], s[38:39], 0, v[82:83]
	v_lshl_add_u64 v[82:83], v[82:83], 0, v[152:153]
	s_waitcnt vmcnt(0)
	v_fmamk_f32 v84, v84, 0x3a800000, v159
	v_rsq_f32_e32 v84, v84
	s_nop 0
	v_pk_mul_f32 v[80:81], v[80:81], v[84:85] op_sel_hi:[1,0]
	v_pk_mul_f32 v[78:79], v[78:79], v[84:85] op_sel_hi:[1,0]
	v_pk_mul_f32 v[76:77], v[76:77], v[84:85] op_sel_hi:[1,0]
	v_pk_mul_f32 v[74:75], v[74:75], v[84:85] op_sel_hi:[1,0]
	v_pk_mul_f32 v[72:73], v[72:73], v[84:85] op_sel_hi:[1,0]
	v_pk_mul_f32 v[70:71], v[70:71], v[84:85] op_sel_hi:[1,0]
	v_pk_mul_f32 v[68:69], v[68:69], v[84:85] op_sel_hi:[1,0]
	v_pk_mul_f32 v[66:67], v[66:67], v[84:85] op_sel_hi:[1,0]
	v_max_f32_e32 v78, 0, v78
	v_max_f32_e32 v74, 0, v74
	v_max_f32_e32 v79, 0, v79
	v_max_f32_e32 v75, 0, v75
	v_max_f32_e32 v80, 0, v80
	v_max_f32_e32 v76, 0, v76
	v_max_f32_e32 v81, 0, v81
	v_max_f32_e32 v77, 0, v77
	v_max_f32_e32 v70, 0, v70
	v_max_f32_e32 v66, 0, v66
	v_max_f32_e32 v71, 0, v71
	v_max_f32_e32 v67, 0, v67
	v_max_f32_e32 v72, 0, v72
	v_max_f32_e32 v68, 0, v68
	v_max_f32_e32 v73, 0, v73
	v_max_f32_e32 v69, 0, v69
	v_pk_mul_f32 v[78:79], v[78:79], v[78:79]
	v_pk_mul_f32 v[74:75], v[74:75], v[74:75]
	v_pk_mul_f32 v[80:81], v[80:81], v[80:81]
	v_pk_mul_f32 v[76:77], v[76:77], v[76:77]
	v_pk_mul_f32 v[70:71], v[70:71], v[70:71]
	v_pk_mul_f32 v[84:85], v[66:67], v[66:67]
	v_pk_mul_f32 v[72:73], v[72:73], v[72:73]
	v_pk_mul_f32 v[86:87], v[68:69], v[68:69]
	v_cvt_pk_bf16_f32 v66, v78, v79
	v_cvt_pk_bf16_f32 v67, v80, v81
	v_cvt_pk_bf16_f32 v68, v74, v75
	v_cvt_pk_bf16_f32 v69, v76, v77
	v_cvt_pk_bf16_f32 v70, v70, v71
	v_cvt_pk_bf16_f32 v71, v72, v73
	v_cvt_pk_bf16_f32 v72, v84, v85
	v_cvt_pk_bf16_f32 v73, v86, v87
	global_store_dwordx4 v[82:83], v[66:69], off sc1
	global_store_dwordx4 v[82:83], v[70:73], off offset:256 sc1
	global_load_dword v68, v[148:149], off offset:512
	v_lshl_add_u64 v[66:67], v[146:147], 0, s[14:15]
	v_add_co_u32_e32 v70, vcc, s54, v146
	s_waitcnt vmcnt(0)
	v_fmamk_f32 v68, v68, 0x3a800000, v159
	v_rsq_f32_e32 v68, v68
	v_addc_co_u32_e32 v71, vcc, 0, v147, vcc
	v_pk_mul_f32 v[64:65], v[64:65], v[68:69] op_sel_hi:[1,0]
	v_pk_mul_f32 v[62:63], v[62:63], v[68:69] op_sel_hi:[1,0]
	v_pk_mul_f32 v[60:61], v[60:61], v[68:69] op_sel_hi:[1,0]
	v_pk_mul_f32 v[58:59], v[58:59], v[68:69] op_sel_hi:[1,0]
	v_pk_mul_f32 v[56:57], v[56:57], v[68:69] op_sel_hi:[1,0]
	v_pk_mul_f32 v[54:55], v[54:55], v[68:69] op_sel_hi:[1,0]
	v_pk_mul_f32 v[52:53], v[52:53], v[68:69] op_sel_hi:[1,0]
	v_pk_mul_f32 v[50:51], v[50:51], v[68:69] op_sel_hi:[1,0]
	v_max_f32_e32 v62, 0, v62
	v_max_f32_e32 v58, 0, v58
	v_max_f32_e32 v63, 0, v63
	v_max_f32_e32 v59, 0, v59
	v_max_f32_e32 v64, 0, v64
	v_max_f32_e32 v60, 0, v60
	v_max_f32_e32 v65, 0, v65
	v_max_f32_e32 v61, 0, v61
	v_max_f32_e32 v54, 0, v54
	v_max_f32_e32 v50, 0, v50
	v_max_f32_e32 v55, 0, v55
	v_max_f32_e32 v51, 0, v51
	v_max_f32_e32 v56, 0, v56
	v_max_f32_e32 v52, 0, v52
	v_max_f32_e32 v57, 0, v57
	v_max_f32_e32 v53, 0, v53
	v_pk_mul_f32 v[62:63], v[62:63], v[62:63]
	v_pk_mul_f32 v[58:59], v[58:59], v[58:59]
	v_pk_mul_f32 v[64:65], v[64:65], v[64:65]
	v_pk_mul_f32 v[60:61], v[60:61], v[60:61]
	v_pk_mul_f32 v[54:55], v[54:55], v[54:55]
	v_pk_mul_f32 v[68:69], v[50:51], v[50:51]
	v_pk_mul_f32 v[56:57], v[56:57], v[56:57]
	v_pk_mul_f32 v[72:73], v[52:53], v[52:53]
	v_cvt_pk_bf16_f32 v50, v62, v63
	v_cvt_pk_bf16_f32 v51, v64, v65
	v_cvt_pk_bf16_f32 v52, v58, v59
	v_cvt_pk_bf16_f32 v53, v60, v61
	v_cvt_pk_bf16_f32 v54, v54, v55
	v_cvt_pk_bf16_f32 v55, v56, v57
	v_cvt_pk_bf16_f32 v56, v68, v69
	v_cvt_pk_bf16_f32 v57, v72, v73
	global_store_dwordx4 v[70:71], v[50:53], off sc1
	global_store_dwordx4 v[66:67], v[54:57], off offset:256 sc1
	global_load_dword v52, v[148:149], off offset:576
	v_lshl_add_u64 v[50:51], v[146:147], 0, s[16:17]
	v_add_co_u32_e32 v54, vcc, s55, v146
	s_waitcnt vmcnt(0)
	v_fmamk_f32 v52, v52, 0x3a800000, v159
	v_rsq_f32_e32 v52, v52
	v_addc_co_u32_e32 v55, vcc, 0, v147, vcc
	v_pk_mul_f32 v[48:49], v[48:49], v[52:53] op_sel_hi:[1,0]
	v_pk_mul_f32 v[46:47], v[46:47], v[52:53] op_sel_hi:[1,0]
	v_pk_mul_f32 v[44:45], v[44:45], v[52:53] op_sel_hi:[1,0]
	v_pk_mul_f32 v[42:43], v[42:43], v[52:53] op_sel_hi:[1,0]
	v_pk_mul_f32 v[40:41], v[40:41], v[52:53] op_sel_hi:[1,0]
	v_pk_mul_f32 v[38:39], v[38:39], v[52:53] op_sel_hi:[1,0]
	v_pk_mul_f32 v[36:37], v[36:37], v[52:53] op_sel_hi:[1,0]
	v_pk_mul_f32 v[34:35], v[34:35], v[52:53] op_sel_hi:[1,0]
	v_max_f32_e32 v46, 0, v46
	v_max_f32_e32 v42, 0, v42
	v_max_f32_e32 v47, 0, v47
	v_max_f32_e32 v43, 0, v43
	v_max_f32_e32 v48, 0, v48
	v_max_f32_e32 v44, 0, v44
	v_max_f32_e32 v49, 0, v49
	v_max_f32_e32 v45, 0, v45
	v_max_f32_e32 v38, 0, v38
	v_max_f32_e32 v34, 0, v34
	v_max_f32_e32 v39, 0, v39
	v_max_f32_e32 v35, 0, v35
	v_max_f32_e32 v40, 0, v40
	v_max_f32_e32 v36, 0, v36
	v_max_f32_e32 v41, 0, v41
	v_max_f32_e32 v37, 0, v37
	v_pk_mul_f32 v[46:47], v[46:47], v[46:47]
	v_pk_mul_f32 v[42:43], v[42:43], v[42:43]
	v_pk_mul_f32 v[48:49], v[48:49], v[48:49]
	v_pk_mul_f32 v[44:45], v[44:45], v[44:45]
	v_pk_mul_f32 v[38:39], v[38:39], v[38:39]
	v_pk_mul_f32 v[52:53], v[34:35], v[34:35]
	v_pk_mul_f32 v[40:41], v[40:41], v[40:41]
	v_pk_mul_f32 v[56:57], v[36:37], v[36:37]
	v_cvt_pk_bf16_f32 v34, v46, v47
	v_cvt_pk_bf16_f32 v35, v48, v49
	v_cvt_pk_bf16_f32 v36, v42, v43
	v_cvt_pk_bf16_f32 v37, v44, v45
	v_cvt_pk_bf16_f32 v38, v38, v39
	v_cvt_pk_bf16_f32 v39, v40, v41
	v_cvt_pk_bf16_f32 v40, v52, v53
	v_cvt_pk_bf16_f32 v41, v56, v57
	global_store_dwordx4 v[54:55], v[34:37], off sc1
	global_store_dwordx4 v[50:51], v[38:41], off offset:256 sc1
	global_load_dword v36, v[148:149], off offset:640
	v_lshl_add_u64 v[34:35], v[146:147], 0, s[18:19]
	v_add_co_u32_e32 v38, vcc, s56, v146
	s_waitcnt vmcnt(0)
	v_fmamk_f32 v36, v36, 0x3a800000, v159
	v_rsq_f32_e32 v36, v36
	v_addc_co_u32_e32 v39, vcc, 0, v147, vcc
	s_andn2_b64 vcc, exec, s[2:3]
	v_pk_mul_f32 v[32:33], v[32:33], v[36:37] op_sel_hi:[1,0]
	v_pk_mul_f32 v[30:31], v[30:31], v[36:37] op_sel_hi:[1,0]
	v_pk_mul_f32 v[28:29], v[28:29], v[36:37] op_sel_hi:[1,0]
	v_pk_mul_f32 v[26:27], v[26:27], v[36:37] op_sel_hi:[1,0]
	v_pk_mul_f32 v[24:25], v[24:25], v[36:37] op_sel_hi:[1,0]
	v_pk_mul_f32 v[22:23], v[22:23], v[36:37] op_sel_hi:[1,0]
	v_pk_mul_f32 v[20:21], v[20:21], v[36:37] op_sel_hi:[1,0]
	v_pk_mul_f32 v[18:19], v[18:19], v[36:37] op_sel_hi:[1,0]
	v_max_f32_e32 v30, 0, v30
	v_max_f32_e32 v26, 0, v26
	v_max_f32_e32 v31, 0, v31
	v_max_f32_e32 v27, 0, v27
	v_max_f32_e32 v32, 0, v32
	v_max_f32_e32 v28, 0, v28
	v_max_f32_e32 v33, 0, v33
	v_max_f32_e32 v29, 0, v29
	v_max_f32_e32 v22, 0, v22
	v_max_f32_e32 v18, 0, v18
	v_max_f32_e32 v23, 0, v23
	v_max_f32_e32 v19, 0, v19
	v_max_f32_e32 v24, 0, v24
	v_max_f32_e32 v20, 0, v20
	v_max_f32_e32 v25, 0, v25
	v_max_f32_e32 v21, 0, v21
	v_pk_mul_f32 v[30:31], v[30:31], v[30:31]
	v_pk_mul_f32 v[26:27], v[26:27], v[26:27]
	v_pk_mul_f32 v[32:33], v[32:33], v[32:33]
	v_pk_mul_f32 v[28:29], v[28:29], v[28:29]
	v_pk_mul_f32 v[22:23], v[22:23], v[22:23]
	v_pk_mul_f32 v[36:37], v[18:19], v[18:19]
	v_pk_mul_f32 v[24:25], v[24:25], v[24:25]
	v_pk_mul_f32 v[40:41], v[20:21], v[20:21]
	v_cvt_pk_bf16_f32 v18, v30, v31
	v_cvt_pk_bf16_f32 v19, v32, v33
	v_cvt_pk_bf16_f32 v20, v26, v27
	v_cvt_pk_bf16_f32 v21, v28, v29
	v_cvt_pk_bf16_f32 v22, v22, v23
	v_cvt_pk_bf16_f32 v23, v24, v25
	v_cvt_pk_bf16_f32 v24, v36, v37
	v_cvt_pk_bf16_f32 v25, v40, v41
	global_store_dwordx4 v[38:39], v[18:21], off sc1
	global_store_dwordx4 v[34:35], v[22:25], off offset:256 sc1
	global_load_dword v20, v[148:149], off offset:704
	v_lshl_add_u64 v[18:19], v[146:147], 0, s[20:21]
	v_add_co_u32_e64 v22, s[0:1], s57, v146
	s_waitcnt vmcnt(0)
	v_fmamk_f32 v20, v20, 0x3a800000, v159
	v_rsq_f32_e32 v20, v20
	v_addc_co_u32_e64 v23, s[0:1], 0, v147, s[0:1]
	s_mov_b64 s[0:1], -1
	v_pk_mul_f32 v[16:17], v[16:17], v[20:21] op_sel_hi:[1,0]
	v_pk_mul_f32 v[14:15], v[14:15], v[20:21] op_sel_hi:[1,0]
	v_pk_mul_f32 v[12:13], v[12:13], v[20:21] op_sel_hi:[1,0]
	v_pk_mul_f32 v[10:11], v[10:11], v[20:21] op_sel_hi:[1,0]
	v_pk_mul_f32 v[8:9], v[8:9], v[20:21] op_sel_hi:[1,0]
	v_pk_mul_f32 v[6:7], v[6:7], v[20:21] op_sel_hi:[1,0]
	v_pk_mul_f32 v[4:5], v[4:5], v[20:21] op_sel_hi:[1,0]
	v_pk_mul_f32 v[2:3], v[2:3], v[20:21] op_sel_hi:[1,0]
	v_max_f32_e32 v14, 0, v14
	v_max_f32_e32 v10, 0, v10
	v_max_f32_e32 v15, 0, v15
	v_max_f32_e32 v11, 0, v11
	v_max_f32_e32 v16, 0, v16
	v_max_f32_e32 v12, 0, v12
	v_max_f32_e32 v17, 0, v17
	v_max_f32_e32 v13, 0, v13
	v_max_f32_e32 v6, 0, v6
	v_max_f32_e32 v2, 0, v2
	v_max_f32_e32 v7, 0, v7
	v_max_f32_e32 v3, 0, v3
	v_max_f32_e32 v8, 0, v8
	v_max_f32_e32 v4, 0, v4
	v_max_f32_e32 v9, 0, v9
	v_max_f32_e32 v5, 0, v5
	v_pk_mul_f32 v[14:15], v[14:15], v[14:15]
	v_pk_mul_f32 v[10:11], v[10:11], v[10:11]
	v_pk_mul_f32 v[16:17], v[16:17], v[16:17]
	v_pk_mul_f32 v[12:13], v[12:13], v[12:13]
	v_pk_mul_f32 v[6:7], v[6:7], v[6:7]
	v_pk_mul_f32 v[20:21], v[2:3], v[2:3]
	v_pk_mul_f32 v[8:9], v[8:9], v[8:9]
	v_pk_mul_f32 v[24:25], v[4:5], v[4:5]
	v_cvt_pk_bf16_f32 v2, v14, v15
	v_cvt_pk_bf16_f32 v3, v16, v17
	v_cvt_pk_bf16_f32 v4, v10, v11
	v_cvt_pk_bf16_f32 v5, v12, v13
	v_cvt_pk_bf16_f32 v6, v6, v7
	v_cvt_pk_bf16_f32 v7, v8, v9
	v_cvt_pk_bf16_f32 v8, v20, v21
	v_cvt_pk_bf16_f32 v9, v24, v25
	global_store_dwordx4 v[22:23], v[2:5], off sc1
	global_store_dwordx4 v[18:19], v[6:9], off offset:256 sc1
	s_cbranch_vccnz .LBB0_454
	s_andn2_b64 vcc, exec, s[6:7]
	s_cbranch_vccnz .LBB0_453
	s_barrier
	s_branch .LBB0_453

.LBB0_1667:
	v_lshl_add_u32 v150, s0, 8, v1
	v_ashrrev_i32_e32 v151, 31, v150
	v_lshl_add_u64 v[146:147], v[150:151], 2, s[6:7]
	global_load_dword v164, v[146:147], off
	v_lshl_or_b32 v148, s1, 8, v155
	v_ashrrev_i32_e32 v149, 31, v148
	v_lshlrev_b64 v[152:153], 1, v[148:149]
	v_lshlrev_b64 v[162:163], 13, v[150:151]
	v_or_b32_e32 v160, 16, v150
	v_ashrrev_i32_e32 v161, 31, v160
	s_waitcnt vmcnt(0)
	v_fmamk_f32 v148, v164, 0x3a800000, v159
	v_rsq_f32_e32 v164, v148
	v_lshl_add_u64 v[148:149], s[38:39], 0, v[162:163]
	v_lshl_add_u64 v[148:149], v[148:149], 0, v[152:153]
	v_lshl_add_u64 v[162:163], v[160:161], 2, s[6:7]
	v_pk_mul_f32 v[128:129], v[128:129], v[164:165] op_sel_hi:[1,0]
	v_pk_mul_f32 v[126:127], v[126:127], v[164:165] op_sel_hi:[1,0]
	v_pk_mul_f32 v[124:125], v[124:125], v[164:165] op_sel_hi:[1,0]
	v_pk_mul_f32 v[122:123], v[122:123], v[164:165] op_sel_hi:[1,0]
	v_pk_mul_f32 v[120:121], v[120:121], v[164:165] op_sel_hi:[1,0]
	v_pk_mul_f32 v[118:119], v[118:119], v[164:165] op_sel_hi:[1,0]
	v_pk_mul_f32 v[116:117], v[116:117], v[164:165] op_sel_hi:[1,0]
	v_pk_mul_f32 v[114:115], v[114:115], v[164:165] op_sel_hi:[1,0]
	v_max_f32_e32 v126, 0, v126
	v_max_f32_e32 v122, 0, v122
	v_max_f32_e32 v127, 0, v127
	v_max_f32_e32 v123, 0, v123
	v_max_f32_e32 v128, 0, v128
	v_max_f32_e32 v124, 0, v124
	v_max_f32_e32 v129, 0, v129
	v_max_f32_e32 v125, 0, v125
	v_max_f32_e32 v118, 0, v118
	v_max_f32_e32 v114, 0, v114
	v_max_f32_e32 v119, 0, v119
	v_max_f32_e32 v115, 0, v115
	v_max_f32_e32 v120, 0, v120
	v_max_f32_e32 v116, 0, v116
	v_max_f32_e32 v121, 0, v121
	v_max_f32_e32 v117, 0, v117
	v_pk_mul_f32 v[126:127], v[126:127], v[126:127]
	v_pk_mul_f32 v[122:123], v[122:123], v[122:123]
	v_pk_mul_f32 v[128:129], v[128:129], v[128:129]
	v_pk_mul_f32 v[124:125], v[124:125], v[124:125]
	v_pk_mul_f32 v[118:119], v[118:119], v[118:119]
	v_pk_mul_f32 v[164:165], v[114:115], v[114:115]
	v_pk_mul_f32 v[120:121], v[120:121], v[120:121]
	v_pk_mul_f32 v[166:167], v[116:117], v[116:117]
	v_cvt_pk_bf16_f32 v114, v126, v127
	v_cvt_pk_bf16_f32 v115, v128, v129
	v_cvt_pk_bf16_f32 v116, v122, v123
	v_cvt_pk_bf16_f32 v117, v124, v125
	v_cvt_pk_bf16_f32 v118, v118, v119
	v_cvt_pk_bf16_f32 v119, v120, v121
	v_cvt_pk_bf16_f32 v120, v164, v165
	v_cvt_pk_bf16_f32 v121, v166, v167
	global_store_dwordx4 v[148:149], v[114:117], off sc1
	global_store_dwordx4 v[148:149], v[118:121], off offset:256 sc1
	global_load_dword v118, v[162:163], off
	v_lshlrev_b64 v[116:117], 13, v[160:161]
	v_or_b32_e32 v114, 32, v150
	v_lshl_add_u64 v[116:117], s[38:39], 0, v[116:117]
	v_ashrrev_i32_e32 v115, 31, v114
	v_lshl_add_u64 v[116:117], v[116:117], 0, v[152:153]
	v_lshl_add_u64 v[120:121], v[114:115], 2, s[6:7]
	s_waitcnt vmcnt(0)
	v_fmamk_f32 v118, v118, 0x3a800000, v159
	v_rsq_f32_e32 v118, v118
	s_nop 0
	v_pk_mul_f32 v[112:113], v[112:113], v[118:119] op_sel_hi:[1,0]
	v_pk_mul_f32 v[110:111], v[110:111], v[118:119] op_sel_hi:[1,0]
	v_pk_mul_f32 v[108:109], v[108:109], v[118:119] op_sel_hi:[1,0]
	v_pk_mul_f32 v[106:107], v[106:107], v[118:119] op_sel_hi:[1,0]
	v_pk_mul_f32 v[104:105], v[104:105], v[118:119] op_sel_hi:[1,0]
	v_pk_mul_f32 v[102:103], v[102:103], v[118:119] op_sel_hi:[1,0]
	v_pk_mul_f32 v[100:101], v[100:101], v[118:119] op_sel_hi:[1,0]
	v_pk_mul_f32 v[98:99], v[98:99], v[118:119] op_sel_hi:[1,0]
	v_max_f32_e32 v110, 0, v110
	v_max_f32_e32 v106, 0, v106
	v_max_f32_e32 v111, 0, v111
	v_max_f32_e32 v107, 0, v107
	v_max_f32_e32 v112, 0, v112
	v_max_f32_e32 v108, 0, v108
	v_max_f32_e32 v113, 0, v113
	v_max_f32_e32 v109, 0, v109
	v_max_f32_e32 v102, 0, v102
	v_max_f32_e32 v98, 0, v98
	v_max_f32_e32 v103, 0, v103
	v_max_f32_e32 v99, 0, v99
	v_max_f32_e32 v104, 0, v104
	v_max_f32_e32 v100, 0, v100
	v_max_f32_e32 v105, 0, v105
	v_max_f32_e32 v101, 0, v101
	v_pk_mul_f32 v[110:111], v[110:111], v[110:111]
	v_pk_mul_f32 v[106:107], v[106:107], v[106:107]
	v_pk_mul_f32 v[112:113], v[112:113], v[112:113]
	v_pk_mul_f32 v[108:109], v[108:109], v[108:109]
	v_pk_mul_f32 v[102:103], v[102:103], v[102:103]
	v_pk_mul_f32 v[118:119], v[98:99], v[98:99]
	v_pk_mul_f32 v[104:105], v[104:105], v[104:105]
	v_pk_mul_f32 v[122:123], v[100:101], v[100:101]
	v_cvt_pk_bf16_f32 v98, v110, v111
	v_cvt_pk_bf16_f32 v99, v112, v113
	v_cvt_pk_bf16_f32 v100, v106, v107
	v_cvt_pk_bf16_f32 v101, v108, v109
	v_cvt_pk_bf16_f32 v102, v102, v103
	v_cvt_pk_bf16_f32 v103, v104, v105
	v_cvt_pk_bf16_f32 v104, v118, v119
	v_cvt_pk_bf16_f32 v105, v122, v123
	global_store_dwordx4 v[116:117], v[98:101], off sc1
	global_store_dwordx4 v[116:117], v[102:105], off offset:256 sc1
	global_load_dword v102, v[120:121], off
	v_lshlrev_b64 v[100:101], 13, v[114:115]
	v_or_b32_e32 v98, 48, v150
	v_lshl_add_u64 v[100:101], s[38:39], 0, v[100:101]
	v_ashrrev_i32_e32 v99, 31, v98
	v_lshl_add_u64 v[100:101], v[100:101], 0, v[152:153]
	v_lshl_add_u64 v[104:105], v[98:99], 2, s[6:7]
	s_waitcnt vmcnt(0)
	v_fmamk_f32 v102, v102, 0x3a800000, v159
	v_rsq_f32_e32 v102, v102
	s_nop 0
	v_pk_mul_f32 v[96:97], v[96:97], v[102:103] op_sel_hi:[1,0]
	v_pk_mul_f32 v[94:95], v[94:95], v[102:103] op_sel_hi:[1,0]
	v_pk_mul_f32 v[92:93], v[92:93], v[102:103] op_sel_hi:[1,0]
	v_pk_mul_f32 v[90:91], v[90:91], v[102:103] op_sel_hi:[1,0]
	v_pk_mul_f32 v[88:89], v[88:89], v[102:103] op_sel_hi:[1,0]
	v_pk_mul_f32 v[86:87], v[86:87], v[102:103] op_sel_hi:[1,0]
	v_pk_mul_f32 v[84:85], v[84:85], v[102:103] op_sel_hi:[1,0]
	v_pk_mul_f32 v[82:83], v[82:83], v[102:103] op_sel_hi:[1,0]
	v_max_f32_e32 v94, 0, v94
	v_max_f32_e32 v90, 0, v90
	v_max_f32_e32 v95, 0, v95
	v_max_f32_e32 v91, 0, v91
	v_max_f32_e32 v96, 0, v96
	v_max_f32_e32 v92, 0, v92
	v_max_f32_e32 v97, 0, v97
	v_max_f32_e32 v93, 0, v93
	v_max_f32_e32 v86, 0, v86
	v_max_f32_e32 v82, 0, v82
	v_max_f32_e32 v87, 0, v87
	v_max_f32_e32 v83, 0, v83
	v_max_f32_e32 v88, 0, v88
	v_max_f32_e32 v84, 0, v84
	v_max_f32_e32 v89, 0, v89
	v_max_f32_e32 v85, 0, v85
	v_pk_mul_f32 v[94:95], v[94:95], v[94:95]
	v_pk_mul_f32 v[90:91], v[90:91], v[90:91]
	v_pk_mul_f32 v[96:97], v[96:97], v[96:97]
	v_pk_mul_f32 v[92:93], v[92:93], v[92:93]
	v_pk_mul_f32 v[86:87], v[86:87], v[86:87]
	v_pk_mul_f32 v[102:103], v[82:83], v[82:83]
	v_pk_mul_f32 v[88:89], v[88:89], v[88:89]
	v_pk_mul_f32 v[106:107], v[84:85], v[84:85]
	v_cvt_pk_bf16_f32 v82, v94, v95
	v_cvt_pk_bf16_f32 v83, v96, v97
	v_cvt_pk_bf16_f32 v84, v90, v91
	v_cvt_pk_bf16_f32 v85, v92, v93
	v_cvt_pk_bf16_f32 v86, v86, v87
	v_cvt_pk_bf16_f32 v87, v88, v89
	v_cvt_pk_bf16_f32 v88, v102, v103
	v_cvt_pk_bf16_f32 v89, v106, v107
	global_store_dwordx4 v[100:101], v[82:85], off sc1
	global_store_dwordx4 v[100:101], v[86:89], off offset:256 sc1
	global_load_dword v82, v[104:105], off
	v_lshlrev_b64 v[84:85], 13, v[98:99]
	v_lshl_add_u64 v[84:85], s[38:39], 0, v[84:85]
	v_lshl_add_u64 v[84:85], v[84:85], 0, v[152:153]
	s_waitcnt vmcnt(0)
	v_fmamk_f32 v82, v82, 0x3a800000, v159
	v_rsq_f32_e32 v82, v82
	s_nop 0
	v_pk_mul_f32 v[80:81], v[80:81], v[82:83] op_sel_hi:[1,0]
	v_pk_mul_f32 v[78:79], v[78:79], v[82:83] op_sel_hi:[1,0]
	v_pk_mul_f32 v[76:77], v[76:77], v[82:83] op_sel_hi:[1,0]
	v_pk_mul_f32 v[74:75], v[74:75], v[82:83] op_sel_hi:[1,0]
	v_pk_mul_f32 v[72:73], v[72:73], v[82:83] op_sel_hi:[1,0]
	v_pk_mul_f32 v[70:71], v[70:71], v[82:83] op_sel_hi:[1,0]
	v_pk_mul_f32 v[68:69], v[68:69], v[82:83] op_sel_hi:[1,0]
	v_pk_mul_f32 v[66:67], v[66:67], v[82:83] op_sel_hi:[1,0]
	v_max_f32_e32 v78, 0, v78
	v_max_f32_e32 v74, 0, v74
	v_max_f32_e32 v79, 0, v79
	v_max_f32_e32 v75, 0, v75
	v_max_f32_e32 v80, 0, v80
	v_max_f32_e32 v76, 0, v76
	v_max_f32_e32 v81, 0, v81
	v_max_f32_e32 v77, 0, v77
	v_max_f32_e32 v70, 0, v70
	v_max_f32_e32 v66, 0, v66
	v_max_f32_e32 v71, 0, v71
	v_max_f32_e32 v67, 0, v67
	v_max_f32_e32 v72, 0, v72
	v_max_f32_e32 v68, 0, v68
	v_max_f32_e32 v73, 0, v73
	v_max_f32_e32 v69, 0, v69
	v_pk_mul_f32 v[78:79], v[78:79], v[78:79]
	v_pk_mul_f32 v[74:75], v[74:75], v[74:75]
	v_pk_mul_f32 v[80:81], v[80:81], v[80:81]
	v_pk_mul_f32 v[76:77], v[76:77], v[76:77]
	v_pk_mul_f32 v[70:71], v[70:71], v[70:71]
	v_pk_mul_f32 v[82:83], v[66:67], v[66:67]
	v_pk_mul_f32 v[72:73], v[72:73], v[72:73]
	v_pk_mul_f32 v[86:87], v[68:69], v[68:69]
	v_cvt_pk_bf16_f32 v66, v78, v79
	v_cvt_pk_bf16_f32 v67, v80, v81
	v_cvt_pk_bf16_f32 v68, v74, v75
	v_cvt_pk_bf16_f32 v69, v76, v77
	v_cvt_pk_bf16_f32 v70, v70, v71
	v_cvt_pk_bf16_f32 v71, v72, v73
	v_cvt_pk_bf16_f32 v72, v82, v83
	v_cvt_pk_bf16_f32 v73, v86, v87
	global_store_dwordx4 v[84:85], v[66:69], off sc1
	global_store_dwordx4 v[84:85], v[70:73], off offset:256 sc1
	global_load_dword v68, v[146:147], off offset:512
	v_lshl_add_u64 v[66:67], v[148:149], 0, s[16:17]
	v_add_co_u32_e32 v70, vcc, s54, v148
	s_waitcnt vmcnt(0)
	v_fmamk_f32 v68, v68, 0x3a800000, v159
	v_rsq_f32_e32 v68, v68
	v_addc_co_u32_e32 v71, vcc, 0, v149, vcc
	v_pk_mul_f32 v[64:65], v[64:65], v[68:69] op_sel_hi:[1,0]
	v_pk_mul_f32 v[62:63], v[62:63], v[68:69] op_sel_hi:[1,0]
	v_pk_mul_f32 v[60:61], v[60:61], v[68:69] op_sel_hi:[1,0]
	v_pk_mul_f32 v[58:59], v[58:59], v[68:69] op_sel_hi:[1,0]
	v_pk_mul_f32 v[56:57], v[56:57], v[68:69] op_sel_hi:[1,0]
	v_pk_mul_f32 v[54:55], v[54:55], v[68:69] op_sel_hi:[1,0]
	v_pk_mul_f32 v[52:53], v[52:53], v[68:69] op_sel_hi:[1,0]
	v_pk_mul_f32 v[50:51], v[50:51], v[68:69] op_sel_hi:[1,0]
	v_max_f32_e32 v62, 0, v62
	v_max_f32_e32 v58, 0, v58
	v_max_f32_e32 v63, 0, v63
	v_max_f32_e32 v59, 0, v59
	v_max_f32_e32 v64, 0, v64
	v_max_f32_e32 v60, 0, v60
	v_max_f32_e32 v65, 0, v65
	v_max_f32_e32 v61, 0, v61
	v_max_f32_e32 v54, 0, v54
	v_max_f32_e32 v50, 0, v50
	v_max_f32_e32 v55, 0, v55
	v_max_f32_e32 v51, 0, v51
	v_max_f32_e32 v56, 0, v56
	v_max_f32_e32 v52, 0, v52
	v_max_f32_e32 v57, 0, v57
	v_max_f32_e32 v53, 0, v53
	v_pk_mul_f32 v[62:63], v[62:63], v[62:63]
	v_pk_mul_f32 v[58:59], v[58:59], v[58:59]
	v_pk_mul_f32 v[64:65], v[64:65], v[64:65]
	v_pk_mul_f32 v[60:61], v[60:61], v[60:61]
	v_pk_mul_f32 v[54:55], v[54:55], v[54:55]
	v_pk_mul_f32 v[68:69], v[50:51], v[50:51]
	v_pk_mul_f32 v[56:57], v[56:57], v[56:57]
	v_pk_mul_f32 v[72:73], v[52:53], v[52:53]
	v_cvt_pk_bf16_f32 v50, v62, v63
	v_cvt_pk_bf16_f32 v51, v64, v65
	v_cvt_pk_bf16_f32 v52, v58, v59
	v_cvt_pk_bf16_f32 v53, v60, v61
	v_cvt_pk_bf16_f32 v54, v54, v55
	v_cvt_pk_bf16_f32 v55, v56, v57
	v_cvt_pk_bf16_f32 v56, v68, v69
	v_cvt_pk_bf16_f32 v57, v72, v73
	global_store_dwordx4 v[70:71], v[50:53], off sc1
	global_store_dwordx4 v[66:67], v[54:57], off offset:256 sc1
	global_load_dword v52, v[146:147], off offset:576
	v_lshl_add_u64 v[50:51], v[148:149], 0, s[18:19]
	v_add_co_u32_e32 v54, vcc, s55, v148
	s_waitcnt vmcnt(0)
	v_fmamk_f32 v52, v52, 0x3a800000, v159
	v_rsq_f32_e32 v52, v52
	v_addc_co_u32_e32 v55, vcc, 0, v149, vcc
	v_pk_mul_f32 v[48:49], v[48:49], v[52:53] op_sel_hi:[1,0]
	v_pk_mul_f32 v[46:47], v[46:47], v[52:53] op_sel_hi:[1,0]
	v_pk_mul_f32 v[44:45], v[44:45], v[52:53] op_sel_hi:[1,0]
	v_pk_mul_f32 v[42:43], v[42:43], v[52:53] op_sel_hi:[1,0]
	v_pk_mul_f32 v[40:41], v[40:41], v[52:53] op_sel_hi:[1,0]
	v_pk_mul_f32 v[38:39], v[38:39], v[52:53] op_sel_hi:[1,0]
	v_pk_mul_f32 v[36:37], v[36:37], v[52:53] op_sel_hi:[1,0]
	v_pk_mul_f32 v[34:35], v[34:35], v[52:53] op_sel_hi:[1,0]
	v_max_f32_e32 v46, 0, v46
	v_max_f32_e32 v42, 0, v42
	v_max_f32_e32 v47, 0, v47
	v_max_f32_e32 v43, 0, v43
	v_max_f32_e32 v48, 0, v48
	v_max_f32_e32 v44, 0, v44
	v_max_f32_e32 v49, 0, v49
	v_max_f32_e32 v45, 0, v45
	v_max_f32_e32 v38, 0, v38
	v_max_f32_e32 v34, 0, v34
	v_max_f32_e32 v39, 0, v39
	v_max_f32_e32 v35, 0, v35
	v_max_f32_e32 v40, 0, v40
	v_max_f32_e32 v36, 0, v36
	v_max_f32_e32 v41, 0, v41
	v_max_f32_e32 v37, 0, v37
	v_pk_mul_f32 v[46:47], v[46:47], v[46:47]
	v_pk_mul_f32 v[42:43], v[42:43], v[42:43]
	v_pk_mul_f32 v[48:49], v[48:49], v[48:49]
	v_pk_mul_f32 v[44:45], v[44:45], v[44:45]
	v_pk_mul_f32 v[38:39], v[38:39], v[38:39]
	v_pk_mul_f32 v[52:53], v[34:35], v[34:35]
	v_pk_mul_f32 v[40:41], v[40:41], v[40:41]
	v_pk_mul_f32 v[56:57], v[36:37], v[36:37]
	v_cvt_pk_bf16_f32 v34, v46, v47
	v_cvt_pk_bf16_f32 v35, v48, v49
	v_cvt_pk_bf16_f32 v36, v42, v43
	v_cvt_pk_bf16_f32 v37, v44, v45
	v_cvt_pk_bf16_f32 v38, v38, v39
	v_cvt_pk_bf16_f32 v39, v40, v41
	v_cvt_pk_bf16_f32 v40, v52, v53
	v_cvt_pk_bf16_f32 v41, v56, v57
	global_store_dwordx4 v[54:55], v[34:37], off sc1
	global_store_dwordx4 v[50:51], v[38:41], off offset:256 sc1
	global_load_dword v36, v[146:147], off offset:640
	v_lshl_add_u64 v[34:35], v[148:149], 0, s[20:21]
	v_add_co_u32_e32 v38, vcc, s56, v148
	s_waitcnt vmcnt(0)
	v_fmamk_f32 v36, v36, 0x3a800000, v159
	v_rsq_f32_e32 v36, v36
	v_addc_co_u32_e32 v39, vcc, 0, v149, vcc
	s_andn2_b64 vcc, exec, s[2:3]
	v_pk_mul_f32 v[32:33], v[32:33], v[36:37] op_sel_hi:[1,0]
	v_pk_mul_f32 v[30:31], v[30:31], v[36:37] op_sel_hi:[1,0]
	v_pk_mul_f32 v[28:29], v[28:29], v[36:37] op_sel_hi:[1,0]
	v_pk_mul_f32 v[26:27], v[26:27], v[36:37] op_sel_hi:[1,0]
	v_pk_mul_f32 v[24:25], v[24:25], v[36:37] op_sel_hi:[1,0]
	v_pk_mul_f32 v[22:23], v[22:23], v[36:37] op_sel_hi:[1,0]
	v_pk_mul_f32 v[20:21], v[20:21], v[36:37] op_sel_hi:[1,0]
	v_pk_mul_f32 v[18:19], v[18:19], v[36:37] op_sel_hi:[1,0]
	v_max_f32_e32 v30, 0, v30
	v_max_f32_e32 v26, 0, v26
	v_max_f32_e32 v31, 0, v31
	v_max_f32_e32 v27, 0, v27
	v_max_f32_e32 v32, 0, v32
	v_max_f32_e32 v28, 0, v28
	v_max_f32_e32 v33, 0, v33
	v_max_f32_e32 v29, 0, v29
	v_max_f32_e32 v22, 0, v22
	v_max_f32_e32 v18, 0, v18
	v_max_f32_e32 v23, 0, v23
	v_max_f32_e32 v19, 0, v19
	v_max_f32_e32 v24, 0, v24
	v_max_f32_e32 v20, 0, v20
	v_max_f32_e32 v25, 0, v25
	v_max_f32_e32 v21, 0, v21
	v_pk_mul_f32 v[30:31], v[30:31], v[30:31]
	v_pk_mul_f32 v[26:27], v[26:27], v[26:27]
	v_pk_mul_f32 v[32:33], v[32:33], v[32:33]
	v_pk_mul_f32 v[28:29], v[28:29], v[28:29]
	v_pk_mul_f32 v[22:23], v[22:23], v[22:23]
	v_pk_mul_f32 v[36:37], v[18:19], v[18:19]
	v_pk_mul_f32 v[24:25], v[24:25], v[24:25]
	v_pk_mul_f32 v[40:41], v[20:21], v[20:21]
	v_cvt_pk_bf16_f32 v18, v30, v31
	v_cvt_pk_bf16_f32 v19, v32, v33
	v_cvt_pk_bf16_f32 v20, v26, v27
	v_cvt_pk_bf16_f32 v21, v28, v29
	v_cvt_pk_bf16_f32 v22, v22, v23
	v_cvt_pk_bf16_f32 v23, v24, v25
	v_cvt_pk_bf16_f32 v24, v36, v37
	v_cvt_pk_bf16_f32 v25, v40, v41
	global_store_dwordx4 v[38:39], v[18:21], off sc1
	global_store_dwordx4 v[34:35], v[22:25], off offset:256 sc1
	global_load_dword v20, v[146:147], off offset:704
	v_lshl_add_u64 v[18:19], v[148:149], 0, s[22:23]
	v_add_co_u32_e64 v22, s[0:1], s57, v148
	s_waitcnt vmcnt(0)
	v_fmamk_f32 v20, v20, 0x3a800000, v159
	v_rsq_f32_e32 v20, v20
	v_addc_co_u32_e64 v23, s[0:1], 0, v149, s[0:1]
	s_mov_b64 s[0:1], -1
	v_pk_mul_f32 v[16:17], v[16:17], v[20:21] op_sel_hi:[1,0]
	v_pk_mul_f32 v[14:15], v[14:15], v[20:21] op_sel_hi:[1,0]
	v_pk_mul_f32 v[12:13], v[12:13], v[20:21] op_sel_hi:[1,0]
	v_pk_mul_f32 v[10:11], v[10:11], v[20:21] op_sel_hi:[1,0]
	v_pk_mul_f32 v[8:9], v[8:9], v[20:21] op_sel_hi:[1,0]
	v_pk_mul_f32 v[6:7], v[6:7], v[20:21] op_sel_hi:[1,0]
	v_pk_mul_f32 v[4:5], v[4:5], v[20:21] op_sel_hi:[1,0]
	v_pk_mul_f32 v[2:3], v[2:3], v[20:21] op_sel_hi:[1,0]
	v_max_f32_e32 v14, 0, v14
	v_max_f32_e32 v10, 0, v10
	v_max_f32_e32 v15, 0, v15
	v_max_f32_e32 v11, 0, v11
	v_max_f32_e32 v16, 0, v16
	v_max_f32_e32 v12, 0, v12
	v_max_f32_e32 v17, 0, v17
	v_max_f32_e32 v13, 0, v13
	v_max_f32_e32 v6, 0, v6
	v_max_f32_e32 v2, 0, v2
	v_max_f32_e32 v7, 0, v7
	v_max_f32_e32 v3, 0, v3
	v_max_f32_e32 v8, 0, v8
	v_max_f32_e32 v4, 0, v4
	v_max_f32_e32 v9, 0, v9
	v_max_f32_e32 v5, 0, v5
	v_pk_mul_f32 v[14:15], v[14:15], v[14:15]
	v_pk_mul_f32 v[10:11], v[10:11], v[10:11]
	v_pk_mul_f32 v[16:17], v[16:17], v[16:17]
	v_pk_mul_f32 v[12:13], v[12:13], v[12:13]
	v_pk_mul_f32 v[6:7], v[6:7], v[6:7]
	v_pk_mul_f32 v[20:21], v[2:3], v[2:3]
	v_pk_mul_f32 v[8:9], v[8:9], v[8:9]
	v_pk_mul_f32 v[24:25], v[4:5], v[4:5]
	v_cvt_pk_bf16_f32 v2, v14, v15
	v_cvt_pk_bf16_f32 v3, v16, v17
	v_cvt_pk_bf16_f32 v4, v10, v11
	v_cvt_pk_bf16_f32 v5, v12, v13
	v_cvt_pk_bf16_f32 v6, v6, v7
	v_cvt_pk_bf16_f32 v7, v8, v9
	v_cvt_pk_bf16_f32 v8, v20, v21
	v_cvt_pk_bf16_f32 v9, v24, v25
	global_store_dwordx4 v[22:23], v[2:5], off sc1
	global_store_dwordx4 v[18:19], v[6:9], off offset:256 sc1
	s_cbranch_vccnz .LBB0_1656
	s_andn2_b64 vcc, exec, s[8:9]
	s_cbranch_vccnz .LBB0_1655
	s_barrier
	s_branch .LBB0_1655
